# SSM pass 2 carry-in: powers of A^512 from a per-item LDS table (built once by all threads) instead of per-lane binary exponentiation in every wave; W loads double-buffered
# speedup vs baseline: 1.0152x; 1.0042x over previous
; template <bool PASS2>
; __device__ __forceinline__ void ssm_phase(const Params& p, const Frame& F0) {
;     ...
;         if (PASS2 && wch > 0) {
;             const float* wb = Wst + (size_t)((g * 2 + b) * 32) * 128;
; #pragma unroll
;             for (int i = 0; i < 4; ++i) {
;                 __builtin_amdgcn_sched_barrier(0);
;                 const f32x4 ma = m1t[8 * i], mb = m1t[8 * i + 1];
;                 float pr_[4] = {ma[0], ma[2], mb[0], mb[2]}, pi_[4] = {ma[1], ma[3], mb[1], mb[3]};
; #pragma unroll
;                 for (int r = 0; r < 4; ++r) {
; #pragma unroll
;                     for (int s2 = 0; s2 < 6; ++s2) { const float nr = pr_[r] * pr_[r] - pi_[r] * pi_[r], ni = 2.f * pr_[r] * pi_[r]; pr_[r] = nr; pi_[r] = ni; } }
;                 f32x4 wre[2], wim[2]; int ex[2];
; #pragma unroll
;                 for (int e = 0; e < 2; ++e) { const int w = j + 16 * e; const bool ok = w < wch; ex[e] = ok ? (wch - 1 - w) : 0; const int wc_ = ok ? w : 0;
;                     const f32x4 lr = *(const f32x4*)(wb + wc_ * 128 + 16 * i + 4 * gq), li = *(const f32x4*)(wb + wc_ * 128 + 64 + 16 * i + 4 * gq);
;                     wre[e] = ok ? lr : (f32x4){0.f, 0.f, 0.f, 0.f}; wim[e] = ok ? li : (f32x4){0.f, 0.f, 0.f, 0.f}; }
.LBB0_612:
	s_or_b64 exec, exec, s[16:17]
	s_ashr_i32 s43, s90, 5
	s_lshl_b32 s0, s43, 3
	s_and_b32 s42, s0, 24
	s_ashr_i32 s0, s90, 7
	s_add_i32 s42, s42, s87
	s_cmp_gt_i32 s42, 0
	s_mov_b64 s[16:17], -1
	s_waitcnt lgkmcnt(0)
	s_barrier
	v_and_b32_e32 v20, 63, v202
	v_lshl_add_u32 v21, v20, 3, s88
	ds_read_b64 v[22:23], v21
	v_readfirstlane_b32 s36, v202
	v_and_b32_e32 v24, 1, v20
	v_lshlrev_b32_e32 v24, 2, v24
	v_sub_u32_e32 v36, v21, v24
	s_lshr_b32 s36, s36, 6
	s_lshl_b32 s37, s36, 11
	v_add_u32_e32 v36, s37, v36
	s_waitcnt lgkmcnt(0)
	v_mul_f32_e32 v24, v23, v23
	v_add_f32_e32 v25, v22, v22
	v_fma_f32 v22, v22, v22, -v24
	v_mul_f32_e32 v23, v25, v23
	v_mul_f32_e32 v24, v23, v23
	v_add_f32_e32 v25, v22, v22
	v_fma_f32 v22, v22, v22, -v24
	v_mul_f32_e32 v23, v25, v23
	v_mul_f32_e32 v24, v23, v23
	v_add_f32_e32 v25, v22, v22
	v_fma_f32 v22, v22, v22, -v24
	v_mul_f32_e32 v23, v25, v23
	v_mul_f32_e32 v24, v23, v23
	v_add_f32_e32 v25, v22, v22
	v_fma_f32 v22, v22, v22, -v24
	v_mul_f32_e32 v23, v25, v23
	v_mul_f32_e32 v24, v23, v23
	v_add_f32_e32 v25, v22, v22
	v_fma_f32 v22, v22, v22, -v24
	v_mul_f32_e32 v23, v25, v23
	v_mul_f32_e32 v24, v23, v23
	v_add_f32_e32 v25, v22, v22
	v_fma_f32 v22, v22, v22, -v24
	v_mul_f32_e32 v23, v25, v23
	v_mov_b32_e32 v26, v22
	v_mov_b32_e32 v27, v23
	v_mul_f32_e32 v24, v23, v23
	v_add_f32_e32 v25, v22, v22
	v_fma_f32 v22, v22, v22, -v24
	v_mul_f32_e32 v23, v25, v23
	v_mul_f32_e32 v24, v23, v23
	v_add_f32_e32 v25, v22, v22
	v_fma_f32 v22, v22, v22, -v24
	v_mul_f32_e32 v23, v25, v23
	v_mov_b32_e32 v28, v22
	v_mov_b32_e32 v29, v23
	v_mul_f32_e32 v24, v23, v23
	v_add_f32_e32 v25, v22, v22
	v_fma_f32 v22, v22, v22, -v24
	v_mul_f32_e32 v23, v25, v23
	v_mov_b32_e32 v30, v22
	v_mov_b32_e32 v31, v23
	v_mul_f32_e32 v24, v23, v23
	v_add_f32_e32 v25, v22, v22
	v_fma_f32 v22, v22, v22, -v24
	v_mul_f32_e32 v23, v25, v23
	v_mov_b32_e32 v34, 1.0
	v_mov_b32_e32 v35, 0
	s_bitcmp1_b32 s36, 0
	s_cbranch_scc0 .Lp3t_0
	v_mul_f32_e32 v24, v35, v29
	v_mul_f32_e32 v25, v34, v29
	v_fma_f32 v34, v34, v28, -v24
	v_fma_f32 v35, v35, v28, v25
.Lp3t_0:
	s_bitcmp1_b32 s36, 1
	s_cbranch_scc0 .Lp3t_1
	v_mul_f32_e32 v24, v35, v31
	v_mul_f32_e32 v25, v34, v31
	v_fma_f32 v34, v34, v30, -v24
	v_fma_f32 v35, v35, v30, v25
.Lp3t_1:
	s_bitcmp1_b32 s36, 2
	s_cbranch_scc0 .Lp3t_2
	v_mul_f32_e32 v24, v35, v23
	v_mul_f32_e32 v25, v34, v23
	v_fma_f32 v34, v34, v22, -v24
	v_fma_f32 v35, v35, v22, v25
.Lp3t_2:
	ds_write_b32 v36, v34 offset:2048
	ds_write_b32 v36, v35 offset:2056
	v_mul_f32_e32 v24, v35, v27
	v_mul_f32_e32 v25, v34, v27
	v_fma_f32 v34, v34, v26, -v24
	v_fma_f32 v35, v35, v26, v25
	ds_write_b32 v36, v34 offset:2560
	ds_write_b32 v36, v35 offset:2568
	v_mul_f32_e32 v24, v35, v27
	v_mul_f32_e32 v25, v34, v27
	v_fma_f32 v34, v34, v26, -v24
	v_fma_f32 v35, v35, v26, v25
	ds_write_b32 v36, v34 offset:3072
	ds_write_b32 v36, v35 offset:3080
	v_mul_f32_e32 v24, v35, v27
	v_mul_f32_e32 v25, v34, v27
	v_fma_f32 v34, v34, v26, -v24
	v_fma_f32 v35, v35, v26, v25
	ds_write_b32 v36, v34 offset:3584
	ds_write_b32 v36, v35 offset:3592
	s_waitcnt lgkmcnt(0)
	s_barrier
	s_cmp_gt_i32 s42, 0
	s_cbranch_scc1 .LBB0_614
	s_lshl_b32 s72, s0, 5
	s_mov_b64 s[16:17], 0
.LBB0_614:
	v_add_u32_e32 v1, 0, v158
	s_andn2_b64 vcc, exec, s[16:17]
	v_add_u32_e32 v198, 0x18000, v1
	s_cbranch_vccnz .LBB0_632
	s_lshl_b32 s16, s3, 6
	s_lshl_b32 s72, s0, 5
	s_add_i32 s16, s16, s72
	s_ashr_i32 s17, s16, 31
	s_lshl_b64 s[16:17], s[16:17], 9
	s_add_u32 s70, s66, s16
	s_addc_u32 s71, s67, s17
	v_cmp_gt_i32_e64 s[36:37], s42, v95
	v_cmp_gt_i32_e64 s[38:39], s42, v162
	v_lshlrev_b32_e32 v2, 9, v95
	v_lshl_add_u32 v2, v94, 2, v2
	v_mov_b32_e32 v3, 0
	s_mov_b64 s[40:41], 0x2000
	v_lshl_add_u64 v[52:53], s[70:71], 0, v[2:3]
	v_lshl_add_u64 v[54:55], v[52:53], 0, s[40:41]
	s_add_i32 s40, s42, -1
	v_sub_u32_e32 v56, s40, v95
	v_max_i32_e32 v56, 0, v56
	v_add_u32_e32 v57, -16, v56
	v_max_i32_e32 v57, 0, v57
	v_lshl_add_u32 v56, v56, 9, v198
	v_lshl_add_u32 v57, v57, 9, v198
	v_mov_b64_e32 v[58:59], 0
	v_mov_b64_e32 v[60:61], 0
	v_mov_b64_e32 v[62:63], 0
	v_mov_b64_e32 v[64:65], 0
	v_mov_b64_e32 v[66:67], 0
	v_mov_b64_e32 v[68:69], 0
	v_mov_b64_e32 v[70:71], 0
	v_mov_b64_e32 v[72:73], 0
	s_and_saveexec_b64 s[16:17], s[36:37]
	global_load_dwordx4 v[58:61], v[52:53], off
	global_load_dwordx4 v[62:65], v[52:53], off offset:256
	s_mov_b64 exec, s[16:17]
	s_and_saveexec_b64 s[16:17], s[38:39]
	global_load_dwordx4 v[66:69], v[54:55], off
	global_load_dwordx4 v[70:73], v[54:55], off offset:256
	s_mov_b64 exec, s[16:17]
	s_nop 4
	v_mov_b64_e32 v[74:75], 0
	v_mov_b64_e32 v[76:77], 0
	v_mov_b64_e32 v[78:79], 0
	v_mov_b64_e32 v[80:81], 0
	v_mov_b64_e32 v[82:83], 0
	v_mov_b64_e32 v[84:85], 0
	v_mov_b64_e32 v[86:87], 0
	v_mov_b64_e32 v[88:89], 0
	s_and_saveexec_b64 s[16:17], s[36:37]
	global_load_dwordx4 v[74:77], v[52:53], off offset:64
	global_load_dwordx4 v[78:81], v[52:53], off offset:320
	s_mov_b64 exec, s[16:17]
	s_and_saveexec_b64 s[16:17], s[38:39]
	global_load_dwordx4 v[82:85], v[54:55], off offset:64
	global_load_dwordx4 v[86:89], v[54:55], off offset:320
	s_mov_b64 exec, s[16:17]
	s_nop 4
	ds_read_b128 v[130:133], v56 offset:2048
	ds_read_b128 v[134:137], v56 offset:2064
	ds_read_b128 v[138:141], v57 offset:2048
	ds_read_b128 v[142:145], v57 offset:2064
	s_waitcnt vmcnt(4) lgkmcnt(0)
; template <bool PASS2>
; __device__ __forceinline__ void ssm_phase(const Params& p, const Frame& F0) {
;     ...
;                 for (int e = 0; e < 2; ++e) { const int w = j + 16 * e; const bool ok = w < wch; ex[e] = ok ? (wch - 1 - w) : 0; const int wc_ = ok ? w : 0;
;                     const f32x4 lr = *(const f32x4*)(wb + wc_ * 128 + 16 * i + 4 * gq), li = *(const f32x4*)(wb + wc_ * 128 + 64 + 16 * i + 4 * gq);
;                     wre[e] = ok ? lr : (f32x4){0.f, 0.f, 0.f, 0.f}; wim[e] = ok ? li : (f32x4){0.f, 0.f, 0.f, 0.f}; }
;                 float fr_[2][4], fi_[2][4];
; #pragma unroll
;                 for (int e = 0; e < 2; ++e)
; #pragma unroll
;                     for (int r = 0; r < 4; ++r) { fr_[e][r] = 1.f; fi_[e][r] = 0.f; }
; #pragma unroll
;                 for (int bit = 0; bit < 5; ++bit) {
; #pragma unroll
;                     for (int e = 0; e < 2; ++e) { const bool on = (ex[e] >> bit) & 1;
; #pragma unroll
;                         for (int r = 0; r < 4; ++r) { const float qr = on ? pr_[r] : 1.f, qi = on ? pi_[r] : 0.f;
;                             const float nr = fr_[e][r] * qr - fi_[e][r] * qi, ni = fr_[e][r] * qi + fi_[e][r] * qr; fr_[e][r] = nr; fi_[e][r] = ni; } }
;                     if (bit < 4) {
; #pragma unroll
;                         for (int r = 0; r < 4; ++r) { const float nr = pr_[r] * pr_[r] - pi_[r] * pi_[r], ni = 2.f * pr_[r] * pi_[r]; pr_[r] = nr; pi_[r] = ni; } }
;                 }
;                 f32x4 hr, hi;
; #pragma unroll
;                 for (int r = 0; r < 4; ++r) { hr[r] = fr_[0][r] * wre[0][r] - fi_[0][r] * wim[0][r] + fr_[1][r] * wre[1][r] - fi_[1][r] * wim[1][r];
;                                               hi[r] = fr_[0][r] * wim[0][r] + fi_[0][r] * wre[0][r] + fr_[1][r] * wim[1][r] + fi_[1][r] * wre[1][r]; }
; #pragma unroll
;                 for (int r = 0; r < 4; ++r) { hr[r] += dppf<DPP_SHR(1)>(hr[r]); hi[r] += dppf<DPP_SHR(1)>(hi[r]); hr[r] += dppf<DPP_SHR(2)>(hr[r]); hi[r] += dppf<DPP_SHR(2)>(hi[r]);
;                                               hr[r] += dppf<DPP_SHR(4)>(hr[r]); hi[r] += dppf<DPP_SHR(4)>(hi[r]); hr[r] += dppf<DPP_SHR(8)>(hr[r]); hi[r] += dppf<DPP_SHR(8)>(hi[r]); }
;                 xs[i] = hr; xs[i + 4] = hi;
	v_pk_mul_f32 v[36:37], v[130:131], v[58:59]
	v_pk_mul_f32 v[40:41], v[130:131], v[62:63]
	v_pk_mul_f32 v[38:39], v[134:135], v[60:61]
	v_pk_mul_f32 v[42:43], v[134:135], v[64:65]
	v_pk_fma_f32 v[36:37], v[132:133], v[62:63], v[36:37] neg_lo:[1,0,0] neg_hi:[1,0,0]
	v_pk_fma_f32 v[40:41], v[132:133], v[58:59], v[40:41]
	v_pk_fma_f32 v[38:39], v[136:137], v[64:65], v[38:39] neg_lo:[1,0,0] neg_hi:[1,0,0]
	v_pk_fma_f32 v[42:43], v[136:137], v[60:61], v[42:43]
	v_pk_fma_f32 v[36:37], v[138:139], v[66:67], v[36:37]
	v_pk_fma_f32 v[40:41], v[138:139], v[70:71], v[40:41]
	v_pk_fma_f32 v[38:39], v[142:143], v[68:69], v[38:39]
	v_pk_fma_f32 v[42:43], v[142:143], v[72:73], v[42:43]
	v_pk_fma_f32 v[36:37], v[140:141], v[70:71], v[36:37] neg_lo:[1,0,0] neg_hi:[1,0,0]
	v_pk_fma_f32 v[40:41], v[140:141], v[66:67], v[40:41]
	v_pk_fma_f32 v[38:39], v[144:145], v[72:73], v[38:39] neg_lo:[1,0,0] neg_hi:[1,0,0]
	v_pk_fma_f32 v[42:43], v[144:145], v[68:69], v[42:43]
	v_mov_b64_e32 v[58:59], 0
	v_mov_b64_e32 v[60:61], 0
	v_mov_b64_e32 v[62:63], 0
	v_mov_b64_e32 v[64:65], 0
	v_mov_b64_e32 v[66:67], 0
	v_mov_b64_e32 v[68:69], 0
	v_mov_b64_e32 v[70:71], 0
	v_mov_b64_e32 v[72:73], 0
	s_and_saveexec_b64 s[16:17], s[36:37]
	global_load_dwordx4 v[58:61], v[52:53], off offset:128
	global_load_dwordx4 v[62:65], v[52:53], off offset:384
	s_mov_b64 exec, s[16:17]
	s_and_saveexec_b64 s[16:17], s[38:39]
	global_load_dwordx4 v[66:69], v[54:55], off offset:128
	global_load_dwordx4 v[70:73], v[54:55], off offset:384
	s_mov_b64 exec, s[16:17]
	s_nop 4
	v_add_f32_dpp v36, v36, v36 row_shr:1 row_mask:0xf bank_mask:0xf bound_ctrl:1
	v_add_f32_dpp v37, v37, v37 row_shr:1 row_mask:0xf bank_mask:0xf bound_ctrl:1
	v_add_f32_dpp v40, v40, v40 row_shr:1 row_mask:0xf bank_mask:0xf bound_ctrl:1
	v_add_f32_dpp v41, v41, v41 row_shr:1 row_mask:0xf bank_mask:0xf bound_ctrl:1
	v_add_f32_dpp v38, v38, v38 row_shr:1 row_mask:0xf bank_mask:0xf bound_ctrl:1
	v_add_f32_dpp v39, v39, v39 row_shr:1 row_mask:0xf bank_mask:0xf bound_ctrl:1
	v_add_f32_dpp v42, v42, v42 row_shr:1 row_mask:0xf bank_mask:0xf bound_ctrl:1
	v_add_f32_dpp v43, v43, v43 row_shr:1 row_mask:0xf bank_mask:0xf bound_ctrl:1
	v_add_f32_dpp v36, v36, v36 row_shr:2 row_mask:0xf bank_mask:0xf bound_ctrl:1
	v_add_f32_dpp v37, v37, v37 row_shr:2 row_mask:0xf bank_mask:0xf bound_ctrl:1
	v_add_f32_dpp v40, v40, v40 row_shr:2 row_mask:0xf bank_mask:0xf bound_ctrl:1
	v_add_f32_dpp v41, v41, v41 row_shr:2 row_mask:0xf bank_mask:0xf bound_ctrl:1
	v_add_f32_dpp v38, v38, v38 row_shr:2 row_mask:0xf bank_mask:0xf bound_ctrl:1
	v_add_f32_dpp v39, v39, v39 row_shr:2 row_mask:0xf bank_mask:0xf bound_ctrl:1
	v_add_f32_dpp v42, v42, v42 row_shr:2 row_mask:0xf bank_mask:0xf bound_ctrl:1
	v_add_f32_dpp v43, v43, v43 row_shr:2 row_mask:0xf bank_mask:0xf bound_ctrl:1
	v_add_f32_dpp v36, v36, v36 row_shr:4 row_mask:0xf bank_mask:0xf bound_ctrl:1
	v_add_f32_dpp v37, v37, v37 row_shr:4 row_mask:0xf bank_mask:0xf bound_ctrl:1
	v_add_f32_dpp v40, v40, v40 row_shr:4 row_mask:0xf bank_mask:0xf bound_ctrl:1
	v_add_f32_dpp v41, v41, v41 row_shr:4 row_mask:0xf bank_mask:0xf bound_ctrl:1
	v_add_f32_dpp v38, v38, v38 row_shr:4 row_mask:0xf bank_mask:0xf bound_ctrl:1
	v_add_f32_dpp v39, v39, v39 row_shr:4 row_mask:0xf bank_mask:0xf bound_ctrl:1
	v_add_f32_dpp v42, v42, v42 row_shr:4 row_mask:0xf bank_mask:0xf bound_ctrl:1
	v_add_f32_dpp v43, v43, v43 row_shr:4 row_mask:0xf bank_mask:0xf bound_ctrl:1
	v_add_f32_dpp v36, v36, v36 row_shr:8 row_mask:0xf bank_mask:0xf bound_ctrl:1
	v_add_f32_dpp v37, v37, v37 row_shr:8 row_mask:0xf bank_mask:0xf bound_ctrl:1
	v_add_f32_dpp v40, v40, v40 row_shr:8 row_mask:0xf bank_mask:0xf bound_ctrl:1
	v_add_f32_dpp v41, v41, v41 row_shr:8 row_mask:0xf bank_mask:0xf bound_ctrl:1
	v_add_f32_dpp v38, v38, v38 row_shr:8 row_mask:0xf bank_mask:0xf bound_ctrl:1
	v_add_f32_dpp v39, v39, v39 row_shr:8 row_mask:0xf bank_mask:0xf bound_ctrl:1
	v_add_f32_dpp v42, v42, v42 row_shr:8 row_mask:0xf bank_mask:0xf bound_ctrl:1
	v_add_f32_dpp v43, v43, v43 row_shr:8 row_mask:0xf bank_mask:0xf bound_ctrl:1
	ds_read_b128 v[130:133], v56 offset:2176
	ds_read_b128 v[134:137], v56 offset:2192
	ds_read_b128 v[138:141], v57 offset:2176
	ds_read_b128 v[142:145], v57 offset:2192
	s_waitcnt vmcnt(4) lgkmcnt(0)
; template <bool PASS2>
; __device__ __forceinline__ void ssm_phase(const Params& p, const Frame& F0) {
;     ...
;                 for (int e = 0; e < 2; ++e) { const int w = j + 16 * e; const bool ok = w < wch; ex[e] = ok ? (wch - 1 - w) : 0; const int wc_ = ok ? w : 0;
;                     const f32x4 lr = *(const f32x4*)(wb + wc_ * 128 + 16 * i + 4 * gq), li = *(const f32x4*)(wb + wc_ * 128 + 64 + 16 * i + 4 * gq);
;                     wre[e] = ok ? lr : (f32x4){0.f, 0.f, 0.f, 0.f}; wim[e] = ok ? li : (f32x4){0.f, 0.f, 0.f, 0.f}; }
;                 float fr_[2][4], fi_[2][4];
; #pragma unroll
;                 for (int e = 0; e < 2; ++e)
; #pragma unroll
;                     for (int r = 0; r < 4; ++r) { fr_[e][r] = 1.f; fi_[e][r] = 0.f; }
; #pragma unroll
;                 for (int bit = 0; bit < 5; ++bit) {
; #pragma unroll
;                     for (int e = 0; e < 2; ++e) { const bool on = (ex[e] >> bit) & 1;
; #pragma unroll
;                         for (int r = 0; r < 4; ++r) { const float qr = on ? pr_[r] : 1.f, qi = on ? pi_[r] : 0.f;
;                             const float nr = fr_[e][r] * qr - fi_[e][r] * qi, ni = fr_[e][r] * qi + fi_[e][r] * qr; fr_[e][r] = nr; fi_[e][r] = ni; } }
;                     if (bit < 4) {
; #pragma unroll
;                         for (int r = 0; r < 4; ++r) { const float nr = pr_[r] * pr_[r] - pi_[r] * pi_[r], ni = 2.f * pr_[r] * pi_[r]; pr_[r] = nr; pi_[r] = ni; } }
;                 }
;                 f32x4 hr, hi;
; #pragma unroll
;                 for (int r = 0; r < 4; ++r) { hr[r] = fr_[0][r] * wre[0][r] - fi_[0][r] * wim[0][r] + fr_[1][r] * wre[1][r] - fi_[1][r] * wim[1][r];
;                                               hi[r] = fr_[0][r] * wim[0][r] + fi_[0][r] * wre[0][r] + fr_[1][r] * wim[1][r] + fi_[1][r] * wre[1][r]; }
; #pragma unroll
;                 for (int r = 0; r < 4; ++r) { hr[r] += dppf<DPP_SHR(1)>(hr[r]); hi[r] += dppf<DPP_SHR(1)>(hi[r]); hr[r] += dppf<DPP_SHR(2)>(hr[r]); hi[r] += dppf<DPP_SHR(2)>(hi[r]);
;                                               hr[r] += dppf<DPP_SHR(4)>(hr[r]); hi[r] += dppf<DPP_SHR(4)>(hi[r]); hr[r] += dppf<DPP_SHR(8)>(hr[r]); hi[r] += dppf<DPP_SHR(8)>(hi[r]); }
;                 xs[i] = hr; xs[i + 4] = hi;
	v_pk_mul_f32 v[28:29], v[130:131], v[74:75]
	v_pk_mul_f32 v[32:33], v[130:131], v[78:79]
	v_pk_mul_f32 v[30:31], v[134:135], v[76:77]
	v_pk_mul_f32 v[34:35], v[134:135], v[80:81]
	v_pk_fma_f32 v[28:29], v[132:133], v[78:79], v[28:29] neg_lo:[1,0,0] neg_hi:[1,0,0]
	v_pk_fma_f32 v[32:33], v[132:133], v[74:75], v[32:33]
	v_pk_fma_f32 v[30:31], v[136:137], v[80:81], v[30:31] neg_lo:[1,0,0] neg_hi:[1,0,0]
	v_pk_fma_f32 v[34:35], v[136:137], v[76:77], v[34:35]
	v_pk_fma_f32 v[28:29], v[138:139], v[82:83], v[28:29]
	v_pk_fma_f32 v[32:33], v[138:139], v[86:87], v[32:33]
	v_pk_fma_f32 v[30:31], v[142:143], v[84:85], v[30:31]
	v_pk_fma_f32 v[34:35], v[142:143], v[88:89], v[34:35]
	v_pk_fma_f32 v[28:29], v[140:141], v[86:87], v[28:29] neg_lo:[1,0,0] neg_hi:[1,0,0]
	v_pk_fma_f32 v[32:33], v[140:141], v[82:83], v[32:33]
	v_pk_fma_f32 v[30:31], v[144:145], v[88:89], v[30:31] neg_lo:[1,0,0] neg_hi:[1,0,0]
	v_pk_fma_f32 v[34:35], v[144:145], v[84:85], v[34:35]
	v_mov_b64_e32 v[74:75], 0
	v_mov_b64_e32 v[76:77], 0
	v_mov_b64_e32 v[78:79], 0
	v_mov_b64_e32 v[80:81], 0
	v_mov_b64_e32 v[82:83], 0
	v_mov_b64_e32 v[84:85], 0
	v_mov_b64_e32 v[86:87], 0
	v_mov_b64_e32 v[88:89], 0
	s_and_saveexec_b64 s[16:17], s[36:37]
	global_load_dwordx4 v[74:77], v[52:53], off offset:192
	global_load_dwordx4 v[78:81], v[52:53], off offset:448
	s_mov_b64 exec, s[16:17]
	s_and_saveexec_b64 s[16:17], s[38:39]
	global_load_dwordx4 v[82:85], v[54:55], off offset:192
	global_load_dwordx4 v[86:89], v[54:55], off offset:448
	s_mov_b64 exec, s[16:17]
	s_nop 4
	v_add_f32_dpp v28, v28, v28 row_shr:1 row_mask:0xf bank_mask:0xf bound_ctrl:1
	v_add_f32_dpp v29, v29, v29 row_shr:1 row_mask:0xf bank_mask:0xf bound_ctrl:1
	v_add_f32_dpp v32, v32, v32 row_shr:1 row_mask:0xf bank_mask:0xf bound_ctrl:1
	v_add_f32_dpp v33, v33, v33 row_shr:1 row_mask:0xf bank_mask:0xf bound_ctrl:1
	v_add_f32_dpp v30, v30, v30 row_shr:1 row_mask:0xf bank_mask:0xf bound_ctrl:1
	v_add_f32_dpp v31, v31, v31 row_shr:1 row_mask:0xf bank_mask:0xf bound_ctrl:1
	v_add_f32_dpp v34, v34, v34 row_shr:1 row_mask:0xf bank_mask:0xf bound_ctrl:1
	v_add_f32_dpp v35, v35, v35 row_shr:1 row_mask:0xf bank_mask:0xf bound_ctrl:1
	v_add_f32_dpp v28, v28, v28 row_shr:2 row_mask:0xf bank_mask:0xf bound_ctrl:1
	v_add_f32_dpp v29, v29, v29 row_shr:2 row_mask:0xf bank_mask:0xf bound_ctrl:1
	v_add_f32_dpp v32, v32, v32 row_shr:2 row_mask:0xf bank_mask:0xf bound_ctrl:1
	v_add_f32_dpp v33, v33, v33 row_shr:2 row_mask:0xf bank_mask:0xf bound_ctrl:1
	v_add_f32_dpp v30, v30, v30 row_shr:2 row_mask:0xf bank_mask:0xf bound_ctrl:1
	v_add_f32_dpp v31, v31, v31 row_shr:2 row_mask:0xf bank_mask:0xf bound_ctrl:1
	v_add_f32_dpp v34, v34, v34 row_shr:2 row_mask:0xf bank_mask:0xf bound_ctrl:1
	v_add_f32_dpp v35, v35, v35 row_shr:2 row_mask:0xf bank_mask:0xf bound_ctrl:1
	v_add_f32_dpp v28, v28, v28 row_shr:4 row_mask:0xf bank_mask:0xf bound_ctrl:1
	v_add_f32_dpp v29, v29, v29 row_shr:4 row_mask:0xf bank_mask:0xf bound_ctrl:1
	v_add_f32_dpp v32, v32, v32 row_shr:4 row_mask:0xf bank_mask:0xf bound_ctrl:1
	v_add_f32_dpp v33, v33, v33 row_shr:4 row_mask:0xf bank_mask:0xf bound_ctrl:1
	v_add_f32_dpp v30, v30, v30 row_shr:4 row_mask:0xf bank_mask:0xf bound_ctrl:1
	v_add_f32_dpp v31, v31, v31 row_shr:4 row_mask:0xf bank_mask:0xf bound_ctrl:1
	v_add_f32_dpp v34, v34, v34 row_shr:4 row_mask:0xf bank_mask:0xf bound_ctrl:1
	v_add_f32_dpp v35, v35, v35 row_shr:4 row_mask:0xf bank_mask:0xf bound_ctrl:1
	v_add_f32_dpp v28, v28, v28 row_shr:8 row_mask:0xf bank_mask:0xf bound_ctrl:1
	v_add_f32_dpp v29, v29, v29 row_shr:8 row_mask:0xf bank_mask:0xf bound_ctrl:1
	v_add_f32_dpp v32, v32, v32 row_shr:8 row_mask:0xf bank_mask:0xf bound_ctrl:1
	v_add_f32_dpp v33, v33, v33 row_shr:8 row_mask:0xf bank_mask:0xf bound_ctrl:1
	v_add_f32_dpp v30, v30, v30 row_shr:8 row_mask:0xf bank_mask:0xf bound_ctrl:1
	v_add_f32_dpp v31, v31, v31 row_shr:8 row_mask:0xf bank_mask:0xf bound_ctrl:1
	v_add_f32_dpp v34, v34, v34 row_shr:8 row_mask:0xf bank_mask:0xf bound_ctrl:1
	v_add_f32_dpp v35, v35, v35 row_shr:8 row_mask:0xf bank_mask:0xf bound_ctrl:1
	ds_read_b128 v[130:133], v56 offset:2304
	ds_read_b128 v[134:137], v56 offset:2320
	ds_read_b128 v[138:141], v57 offset:2304
	ds_read_b128 v[142:145], v57 offset:2320
	s_waitcnt vmcnt(4) lgkmcnt(0)
; template <bool PASS2>
; __device__ __forceinline__ void ssm_phase(const Params& p, const Frame& F0) {
;     ...
;                 for (int e = 0; e < 2; ++e) { const int w = j + 16 * e; const bool ok = w < wch; ex[e] = ok ? (wch - 1 - w) : 0; const int wc_ = ok ? w : 0;
;                     const f32x4 lr = *(const f32x4*)(wb + wc_ * 128 + 16 * i + 4 * gq), li = *(const f32x4*)(wb + wc_ * 128 + 64 + 16 * i + 4 * gq);
;                     wre[e] = ok ? lr : (f32x4){0.f, 0.f, 0.f, 0.f}; wim[e] = ok ? li : (f32x4){0.f, 0.f, 0.f, 0.f}; }
;                 float fr_[2][4], fi_[2][4];
; #pragma unroll
;                 for (int e = 0; e < 2; ++e)
; #pragma unroll
;                     for (int r = 0; r < 4; ++r) { fr_[e][r] = 1.f; fi_[e][r] = 0.f; }
; #pragma unroll
;                 for (int bit = 0; bit < 5; ++bit) {
; #pragma unroll
;                     for (int e = 0; e < 2; ++e) { const bool on = (ex[e] >> bit) & 1;
; #pragma unroll
;                         for (int r = 0; r < 4; ++r) { const float qr = on ? pr_[r] : 1.f, qi = on ? pi_[r] : 0.f;
;                             const float nr = fr_[e][r] * qr - fi_[e][r] * qi, ni = fr_[e][r] * qi + fi_[e][r] * qr; fr_[e][r] = nr; fi_[e][r] = ni; } }
;                     if (bit < 4) {
; #pragma unroll
;                         for (int r = 0; r < 4; ++r) { const float nr = pr_[r] * pr_[r] - pi_[r] * pi_[r], ni = 2.f * pr_[r] * pi_[r]; pr_[r] = nr; pi_[r] = ni; } }
;                 }
;                 f32x4 hr, hi;
; #pragma unroll
;                 for (int r = 0; r < 4; ++r) { hr[r] = fr_[0][r] * wre[0][r] - fi_[0][r] * wim[0][r] + fr_[1][r] * wre[1][r] - fi_[1][r] * wim[1][r];
;                                               hi[r] = fr_[0][r] * wim[0][r] + fi_[0][r] * wre[0][r] + fr_[1][r] * wim[1][r] + fi_[1][r] * wre[1][r]; }
; #pragma unroll
;                 for (int r = 0; r < 4; ++r) { hr[r] += dppf<DPP_SHR(1)>(hr[r]); hi[r] += dppf<DPP_SHR(1)>(hi[r]); hr[r] += dppf<DPP_SHR(2)>(hr[r]); hi[r] += dppf<DPP_SHR(2)>(hi[r]);
;                                               hr[r] += dppf<DPP_SHR(4)>(hr[r]); hi[r] += dppf<DPP_SHR(4)>(hi[r]); hr[r] += dppf<DPP_SHR(8)>(hr[r]); hi[r] += dppf<DPP_SHR(8)>(hi[r]); }
;                 xs[i] = hr; xs[i + 4] = hi;
	v_pk_mul_f32 v[20:21], v[130:131], v[58:59]
	v_pk_mul_f32 v[24:25], v[130:131], v[62:63]
	v_pk_mul_f32 v[22:23], v[134:135], v[60:61]
	v_pk_mul_f32 v[26:27], v[134:135], v[64:65]
	v_pk_fma_f32 v[20:21], v[132:133], v[62:63], v[20:21] neg_lo:[1,0,0] neg_hi:[1,0,0]
	v_pk_fma_f32 v[24:25], v[132:133], v[58:59], v[24:25]
	v_pk_fma_f32 v[22:23], v[136:137], v[64:65], v[22:23] neg_lo:[1,0,0] neg_hi:[1,0,0]
	v_pk_fma_f32 v[26:27], v[136:137], v[60:61], v[26:27]
	v_pk_fma_f32 v[20:21], v[138:139], v[66:67], v[20:21]
	v_pk_fma_f32 v[24:25], v[138:139], v[70:71], v[24:25]
	v_pk_fma_f32 v[22:23], v[142:143], v[68:69], v[22:23]
	v_pk_fma_f32 v[26:27], v[142:143], v[72:73], v[26:27]
	v_pk_fma_f32 v[20:21], v[140:141], v[70:71], v[20:21] neg_lo:[1,0,0] neg_hi:[1,0,0]
	v_pk_fma_f32 v[24:25], v[140:141], v[66:67], v[24:25]
	v_pk_fma_f32 v[22:23], v[144:145], v[72:73], v[22:23] neg_lo:[1,0,0] neg_hi:[1,0,0]
	v_pk_fma_f32 v[26:27], v[144:145], v[68:69], v[26:27]
	v_add_f32_dpp v20, v20, v20 row_shr:1 row_mask:0xf bank_mask:0xf bound_ctrl:1
	v_add_f32_dpp v21, v21, v21 row_shr:1 row_mask:0xf bank_mask:0xf bound_ctrl:1
	v_add_f32_dpp v24, v24, v24 row_shr:1 row_mask:0xf bank_mask:0xf bound_ctrl:1
	v_add_f32_dpp v25, v25, v25 row_shr:1 row_mask:0xf bank_mask:0xf bound_ctrl:1
	v_add_f32_dpp v22, v22, v22 row_shr:1 row_mask:0xf bank_mask:0xf bound_ctrl:1
	v_add_f32_dpp v23, v23, v23 row_shr:1 row_mask:0xf bank_mask:0xf bound_ctrl:1
	v_add_f32_dpp v26, v26, v26 row_shr:1 row_mask:0xf bank_mask:0xf bound_ctrl:1
	v_add_f32_dpp v27, v27, v27 row_shr:1 row_mask:0xf bank_mask:0xf bound_ctrl:1
	v_add_f32_dpp v20, v20, v20 row_shr:2 row_mask:0xf bank_mask:0xf bound_ctrl:1
	v_add_f32_dpp v21, v21, v21 row_shr:2 row_mask:0xf bank_mask:0xf bound_ctrl:1
	v_add_f32_dpp v24, v24, v24 row_shr:2 row_mask:0xf bank_mask:0xf bound_ctrl:1
	v_add_f32_dpp v25, v25, v25 row_shr:2 row_mask:0xf bank_mask:0xf bound_ctrl:1
	v_add_f32_dpp v22, v22, v22 row_shr:2 row_mask:0xf bank_mask:0xf bound_ctrl:1
	v_add_f32_dpp v23, v23, v23 row_shr:2 row_mask:0xf bank_mask:0xf bound_ctrl:1
	v_add_f32_dpp v26, v26, v26 row_shr:2 row_mask:0xf bank_mask:0xf bound_ctrl:1
	v_add_f32_dpp v27, v27, v27 row_shr:2 row_mask:0xf bank_mask:0xf bound_ctrl:1
	v_add_f32_dpp v20, v20, v20 row_shr:4 row_mask:0xf bank_mask:0xf bound_ctrl:1
	v_add_f32_dpp v21, v21, v21 row_shr:4 row_mask:0xf bank_mask:0xf bound_ctrl:1
	v_add_f32_dpp v24, v24, v24 row_shr:4 row_mask:0xf bank_mask:0xf bound_ctrl:1
	v_add_f32_dpp v25, v25, v25 row_shr:4 row_mask:0xf bank_mask:0xf bound_ctrl:1
	v_add_f32_dpp v22, v22, v22 row_shr:4 row_mask:0xf bank_mask:0xf bound_ctrl:1
	v_add_f32_dpp v23, v23, v23 row_shr:4 row_mask:0xf bank_mask:0xf bound_ctrl:1
	v_add_f32_dpp v26, v26, v26 row_shr:4 row_mask:0xf bank_mask:0xf bound_ctrl:1
	v_add_f32_dpp v27, v27, v27 row_shr:4 row_mask:0xf bank_mask:0xf bound_ctrl:1
	v_add_f32_dpp v20, v20, v20 row_shr:8 row_mask:0xf bank_mask:0xf bound_ctrl:1
	v_add_f32_dpp v21, v21, v21 row_shr:8 row_mask:0xf bank_mask:0xf bound_ctrl:1
	v_add_f32_dpp v24, v24, v24 row_shr:8 row_mask:0xf bank_mask:0xf bound_ctrl:1
	v_add_f32_dpp v25, v25, v25 row_shr:8 row_mask:0xf bank_mask:0xf bound_ctrl:1
	v_add_f32_dpp v22, v22, v22 row_shr:8 row_mask:0xf bank_mask:0xf bound_ctrl:1
	v_add_f32_dpp v23, v23, v23 row_shr:8 row_mask:0xf bank_mask:0xf bound_ctrl:1
	v_add_f32_dpp v26, v26, v26 row_shr:8 row_mask:0xf bank_mask:0xf bound_ctrl:1
	v_add_f32_dpp v27, v27, v27 row_shr:8 row_mask:0xf bank_mask:0xf bound_ctrl:1
	ds_read_b128 v[130:133], v56 offset:2432
	ds_read_b128 v[134:137], v56 offset:2448
	ds_read_b128 v[138:141], v57 offset:2432
	ds_read_b128 v[142:145], v57 offset:2448
	s_waitcnt vmcnt(0) lgkmcnt(0)
; template <bool PASS2>
; __device__ __forceinline__ void ssm_phase(const Params& p, const Frame& F0) {
;     ...
;                 for (int e = 0; e < 2; ++e) { const int w = j + 16 * e; const bool ok = w < wch; ex[e] = ok ? (wch - 1 - w) : 0; const int wc_ = ok ? w : 0;
;                     const f32x4 lr = *(const f32x4*)(wb + wc_ * 128 + 16 * i + 4 * gq), li = *(const f32x4*)(wb + wc_ * 128 + 64 + 16 * i + 4 * gq);
;                     wre[e] = ok ? lr : (f32x4){0.f, 0.f, 0.f, 0.f}; wim[e] = ok ? li : (f32x4){0.f, 0.f, 0.f, 0.f}; }
;                 float fr_[2][4], fi_[2][4];
; #pragma unroll
;                 for (int e = 0; e < 2; ++e)
; #pragma unroll
;                     for (int r = 0; r < 4; ++r) { fr_[e][r] = 1.f; fi_[e][r] = 0.f; }
; #pragma unroll
;                 for (int bit = 0; bit < 5; ++bit) {
; #pragma unroll
;                     for (int e = 0; e < 2; ++e) { const bool on = (ex[e] >> bit) & 1;
; #pragma unroll
;                         for (int r = 0; r < 4; ++r) { const float qr = on ? pr_[r] : 1.f, qi = on ? pi_[r] : 0.f;
;                             const float nr = fr_[e][r] * qr - fi_[e][r] * qi, ni = fr_[e][r] * qi + fi_[e][r] * qr; fr_[e][r] = nr; fi_[e][r] = ni; } }
;                     if (bit < 4) {
; #pragma unroll
;                         for (int r = 0; r < 4; ++r) { const float nr = pr_[r] * pr_[r] - pi_[r] * pi_[r], ni = 2.f * pr_[r] * pi_[r]; pr_[r] = nr; pi_[r] = ni; } }
;                 }
;                 f32x4 hr, hi;
; #pragma unroll
;                 for (int r = 0; r < 4; ++r) { hr[r] = fr_[0][r] * wre[0][r] - fi_[0][r] * wim[0][r] + fr_[1][r] * wre[1][r] - fi_[1][r] * wim[1][r];
;                                               hi[r] = fr_[0][r] * wim[0][r] + fi_[0][r] * wre[0][r] + fr_[1][r] * wim[1][r] + fi_[1][r] * wre[1][r]; }
; #pragma unroll
;                 for (int r = 0; r < 4; ++r) { hr[r] += dppf<DPP_SHR(1)>(hr[r]); hi[r] += dppf<DPP_SHR(1)>(hi[r]); hr[r] += dppf<DPP_SHR(2)>(hr[r]); hi[r] += dppf<DPP_SHR(2)>(hi[r]);
;                                               hr[r] += dppf<DPP_SHR(4)>(hr[r]); hi[r] += dppf<DPP_SHR(4)>(hi[r]); hr[r] += dppf<DPP_SHR(8)>(hr[r]); hi[r] += dppf<DPP_SHR(8)>(hi[r]); }
;                 xs[i] = hr; xs[i + 4] = hi;
	v_pk_mul_f32 v[44:45], v[130:131], v[74:75]
	v_pk_mul_f32 v[48:49], v[130:131], v[78:79]
	v_pk_mul_f32 v[46:47], v[134:135], v[76:77]
	v_pk_mul_f32 v[50:51], v[134:135], v[80:81]
	v_pk_fma_f32 v[44:45], v[132:133], v[78:79], v[44:45] neg_lo:[1,0,0] neg_hi:[1,0,0]
	v_pk_fma_f32 v[48:49], v[132:133], v[74:75], v[48:49]
	v_pk_fma_f32 v[46:47], v[136:137], v[80:81], v[46:47] neg_lo:[1,0,0] neg_hi:[1,0,0]
	v_pk_fma_f32 v[50:51], v[136:137], v[76:77], v[50:51]
	v_pk_fma_f32 v[44:45], v[138:139], v[82:83], v[44:45]
	v_pk_fma_f32 v[48:49], v[138:139], v[86:87], v[48:49]
	v_pk_fma_f32 v[46:47], v[142:143], v[84:85], v[46:47]
	v_pk_fma_f32 v[50:51], v[142:143], v[88:89], v[50:51]
	v_pk_fma_f32 v[44:45], v[140:141], v[86:87], v[44:45] neg_lo:[1,0,0] neg_hi:[1,0,0]
	v_pk_fma_f32 v[48:49], v[140:141], v[82:83], v[48:49]
	v_pk_fma_f32 v[46:47], v[144:145], v[88:89], v[46:47] neg_lo:[1,0,0] neg_hi:[1,0,0]
	v_pk_fma_f32 v[50:51], v[144:145], v[84:85], v[50:51]
	v_add_f32_dpp v44, v44, v44 row_shr:1 row_mask:0xf bank_mask:0xf bound_ctrl:1
	v_add_f32_dpp v45, v45, v45 row_shr:1 row_mask:0xf bank_mask:0xf bound_ctrl:1
	v_add_f32_dpp v48, v48, v48 row_shr:1 row_mask:0xf bank_mask:0xf bound_ctrl:1
	v_add_f32_dpp v49, v49, v49 row_shr:1 row_mask:0xf bank_mask:0xf bound_ctrl:1
	v_add_f32_dpp v46, v46, v46 row_shr:1 row_mask:0xf bank_mask:0xf bound_ctrl:1
	v_add_f32_dpp v47, v47, v47 row_shr:1 row_mask:0xf bank_mask:0xf bound_ctrl:1
	v_add_f32_dpp v50, v50, v50 row_shr:1 row_mask:0xf bank_mask:0xf bound_ctrl:1
	v_add_f32_dpp v51, v51, v51 row_shr:1 row_mask:0xf bank_mask:0xf bound_ctrl:1
	v_add_f32_dpp v44, v44, v44 row_shr:2 row_mask:0xf bank_mask:0xf bound_ctrl:1
	v_add_f32_dpp v45, v45, v45 row_shr:2 row_mask:0xf bank_mask:0xf bound_ctrl:1
	v_add_f32_dpp v48, v48, v48 row_shr:2 row_mask:0xf bank_mask:0xf bound_ctrl:1
	v_add_f32_dpp v49, v49, v49 row_shr:2 row_mask:0xf bank_mask:0xf bound_ctrl:1
	v_add_f32_dpp v46, v46, v46 row_shr:2 row_mask:0xf bank_mask:0xf bound_ctrl:1
	v_add_f32_dpp v47, v47, v47 row_shr:2 row_mask:0xf bank_mask:0xf bound_ctrl:1
	v_add_f32_dpp v50, v50, v50 row_shr:2 row_mask:0xf bank_mask:0xf bound_ctrl:1
	v_add_f32_dpp v51, v51, v51 row_shr:2 row_mask:0xf bank_mask:0xf bound_ctrl:1
	v_add_f32_dpp v44, v44, v44 row_shr:4 row_mask:0xf bank_mask:0xf bound_ctrl:1
	v_add_f32_dpp v45, v45, v45 row_shr:4 row_mask:0xf bank_mask:0xf bound_ctrl:1
	v_add_f32_dpp v48, v48, v48 row_shr:4 row_mask:0xf bank_mask:0xf bound_ctrl:1
	v_add_f32_dpp v49, v49, v49 row_shr:4 row_mask:0xf bank_mask:0xf bound_ctrl:1
	v_add_f32_dpp v46, v46, v46 row_shr:4 row_mask:0xf bank_mask:0xf bound_ctrl:1
	v_add_f32_dpp v47, v47, v47 row_shr:4 row_mask:0xf bank_mask:0xf bound_ctrl:1
	v_add_f32_dpp v50, v50, v50 row_shr:4 row_mask:0xf bank_mask:0xf bound_ctrl:1
	v_add_f32_dpp v51, v51, v51 row_shr:4 row_mask:0xf bank_mask:0xf bound_ctrl:1
	v_add_f32_dpp v44, v44, v44 row_shr:8 row_mask:0xf bank_mask:0xf bound_ctrl:1
	v_add_f32_dpp v45, v45, v45 row_shr:8 row_mask:0xf bank_mask:0xf bound_ctrl:1
	v_add_f32_dpp v48, v48, v48 row_shr:8 row_mask:0xf bank_mask:0xf bound_ctrl:1
	v_add_f32_dpp v49, v49, v49 row_shr:8 row_mask:0xf bank_mask:0xf bound_ctrl:1
	v_add_f32_dpp v46, v46, v46 row_shr:8 row_mask:0xf bank_mask:0xf bound_ctrl:1
	v_add_f32_dpp v47, v47, v47 row_shr:8 row_mask:0xf bank_mask:0xf bound_ctrl:1
	v_add_f32_dpp v50, v50, v50 row_shr:8 row_mask:0xf bank_mask:0xf bound_ctrl:1
	v_add_f32_dpp v51, v51, v51 row_shr:8 row_mask:0xf bank_mask:0xf bound_ctrl:1
	s_branch .LBB0_633
